# residual GEMM: first four residual quads requested in the last K-loop body after its final counted wait (no loop wait sees them), epilogue waits once and copies them
# speedup vs baseline: 1.0088x; 1.0088x over previous
.Lfw_2:
.LBB0_855:
	s_add_i32 s52, s44, 2
	s_add_u32 s53, s34, 0x80
	s_addc_u32 s45, s35, 0
	s_add_i32 s56, 0, 0x10000
	s_cmp_eq_u32 s48, s44
	s_cselect_b32 s45, s25, s45
	s_cselect_b32 s44, s24, s53
	v_add_u32_e32 v142, s56, v145
	s_cselect_b32 s55, s31, s47
	s_cselect_b32 s54, s30, s46
	s_add_i32 s53, 0, 0x14000
	ds_read_b128 v[138:141], v142
	ds_read_b128 v[148:151], v142 offset:1024
	ds_read_b128 v[152:155], v142 offset:2048
	ds_read_b128 v[156:159], v142 offset:3072
	v_add_u32_e32 v142, s53, v145
	ds_read_b128 v[160:163], v142
	ds_read_b128 v[164:167], v142 offset:1024
	ds_read_b128 v[168:171], v142 offset:2048
	ds_read_b128 v[172:175], v142 offset:3072
	v_lshl_add_u64 v[142:143], s[34:35], 0, v[134:135]
	s_add_i32 m0, s14, 0xc000
	ds_read_b128 v[176:179], v147
	ds_read_b128 v[180:183], v147 offset:1024
	ds_read_b128 v[184:187], v147 offset:2048
	ds_read_b128 v[188:191], v147 offset:3072
	ds_read_b128 v[192:195], v147 offset:4096
	ds_read_b128 v[204:207], v147 offset:5120
	ds_read_b128 v[208:211], v147 offset:6144
	ds_read_b128 v[212:215], v147 offset:7168
	global_load_lds_dwordx4 v[142:143], off
	v_lshl_add_u64 v[142:143], s[34:35], 0, v[136:137]
	s_add_i32 m0, s14, 0xe000
	s_nop 0
	global_load_lds_dwordx4 v[142:143], off
	s_waitcnt vmcnt(8)
	s_waitcnt lgkmcnt(0)
	s_barrier
	s_setprio 1
	s_waitcnt lgkmcnt(0)
	v_mfma_f32_16x16x32_bf16 v[124:127], v[138:141], v[176:179], v[124:127]
	v_mfma_f32_16x16x32_bf16 v[120:123], v[152:155], v[176:179], v[120:123]
	v_mfma_f32_16x16x32_bf16 v[108:111], v[138:141], v[184:187], v[108:111]
	v_mfma_f32_16x16x32_bf16 v[104:107], v[152:155], v[184:187], v[104:107]
	v_mfma_f32_16x16x32_bf16 v[92:95], v[138:141], v[192:195], v[92:95]
	v_mfma_f32_16x16x32_bf16 v[88:91], v[152:155], v[192:195], v[88:91]
	v_mfma_f32_16x16x32_bf16 v[76:79], v[138:141], v[208:211], v[76:79]
	v_mfma_f32_16x16x32_bf16 v[72:75], v[152:155], v[208:211], v[72:75]
	v_mfma_f32_16x16x32_bf16 v[124:127], v[148:151], v[180:183], v[124:127]
	v_mfma_f32_16x16x32_bf16 v[120:123], v[156:159], v[180:183], v[120:123]
	v_mfma_f32_16x16x32_bf16 v[108:111], v[148:151], v[188:191], v[108:111]
	v_mfma_f32_16x16x32_bf16 v[104:107], v[156:159], v[188:191], v[104:107]
	v_mfma_f32_16x16x32_bf16 v[92:95], v[148:151], v[204:207], v[92:95]
	v_mfma_f32_16x16x32_bf16 v[88:91], v[156:159], v[204:207], v[88:91]
	v_mfma_f32_16x16x32_bf16 v[76:79], v[148:151], v[212:215], v[76:79]
	v_mfma_f32_16x16x32_bf16 v[72:75], v[156:159], v[212:215], v[72:75]
	s_setprio 0
	s_setprio 1
	v_mfma_f32_16x16x32_bf16 v[116:119], v[160:163], v[176:179], v[116:119]
	v_mfma_f32_16x16x32_bf16 v[112:115], v[168:171], v[176:179], v[112:115]
	v_mfma_f32_16x16x32_bf16 v[100:103], v[160:163], v[184:187], v[100:103]
	v_mfma_f32_16x16x32_bf16 v[96:99], v[168:171], v[184:187], v[96:99]
	v_mfma_f32_16x16x32_bf16 v[84:87], v[160:163], v[192:195], v[84:87]
	v_mfma_f32_16x16x32_bf16 v[80:83], v[168:171], v[192:195], v[80:83]
	v_mfma_f32_16x16x32_bf16 v[68:71], v[160:163], v[208:211], v[68:71]
	v_mfma_f32_16x16x32_bf16 v[64:67], v[168:171], v[208:211], v[64:67]
	v_mfma_f32_16x16x32_bf16 v[116:119], v[164:167], v[180:183], v[116:119]
	v_mfma_f32_16x16x32_bf16 v[112:115], v[172:175], v[180:183], v[112:115]
	v_mfma_f32_16x16x32_bf16 v[100:103], v[164:167], v[188:191], v[100:103]
	v_mfma_f32_16x16x32_bf16 v[96:99], v[172:175], v[188:191], v[96:99]
	v_mfma_f32_16x16x32_bf16 v[84:87], v[164:167], v[204:207], v[84:87]
	v_mfma_f32_16x16x32_bf16 v[80:83], v[172:175], v[204:207], v[80:83]
	v_mfma_f32_16x16x32_bf16 v[68:71], v[164:167], v[212:215], v[68:71]
	v_mfma_f32_16x16x32_bf16 v[64:67], v[172:175], v[212:215], v[64:67]
	s_setprio 0
	s_barrier
	s_add_i32 s56, s56, s11
	v_lshl_add_u64 v[142:143], s[54:55], 0, v[196:197]
	s_mov_b32 m0, s56
	ds_read_b128 v[176:179], v147 offset:16384
	ds_read_b128 v[180:183], v147 offset:17408
	ds_read_b128 v[184:187], v147 offset:18432
	ds_read_b128 v[188:191], v147 offset:19456
	ds_read_b128 v[192:195], v147 offset:20480
	ds_read_b128 v[204:207], v147 offset:21504
	ds_read_b128 v[208:211], v147 offset:22528
	ds_read_b128 v[212:215], v147 offset:23552
	global_load_lds_dwordx4 v[142:143], off
	s_add_i32 m0, s56, 0x2000
	v_lshl_add_u64 v[216:217], s[54:55], 0, v[128:129]
	s_add_u32 s54, s54, s12
	s_addc_u32 s55, s55, 0
	s_add_i32 s53, s53, s11
	global_load_lds_dwordx4 v[216:217], off
	v_lshl_add_u64 v[218:219], s[54:55], 0, v[196:197]
	s_mov_b32 m0, s53
	v_lshl_add_u64 v[220:221], s[54:55], 0, v[128:129]
	global_load_lds_dwordx4 v[218:219], off
	s_add_i32 m0, s53, 0x2000
	v_lshl_add_u64 v[226:227], s[44:45], 0, v[132:133]
	global_load_lds_dwordx4 v[220:221], off
	s_mov_b32 m0, s14
	v_lshl_add_u64 v[228:229], s[44:45], 0, v[130:131]
	global_load_lds_dwordx4 v[226:227], off
	s_mov_b32 m0, s15
	s_nop 0
	global_load_lds_dwordx4 v[228:229], off
	s_waitcnt vmcnt(8)
	s_waitcnt lgkmcnt(0)
	s_barrier
	s_setprio 1
	s_waitcnt lgkmcnt(0)
	v_mfma_f32_16x16x32_bf16 v[60:63], v[138:141], v[176:179], v[60:63]
	v_mfma_f32_16x16x32_bf16 v[56:59], v[152:155], v[176:179], v[56:59]
	v_mfma_f32_16x16x32_bf16 v[44:47], v[138:141], v[184:187], v[44:47]
	v_mfma_f32_16x16x32_bf16 v[40:43], v[152:155], v[184:187], v[40:43]
	v_mfma_f32_16x16x32_bf16 v[28:31], v[138:141], v[192:195], v[28:31]
	v_mfma_f32_16x16x32_bf16 v[24:27], v[152:155], v[192:195], v[24:27]
	v_mfma_f32_16x16x32_bf16 v[12:15], v[138:141], v[208:211], v[12:15]
	v_mfma_f32_16x16x32_bf16 v[8:11], v[152:155], v[208:211], v[8:11]
	v_mfma_f32_16x16x32_bf16 v[60:63], v[148:151], v[180:183], v[60:63]
	v_mfma_f32_16x16x32_bf16 v[56:59], v[156:159], v[180:183], v[56:59]
	v_mfma_f32_16x16x32_bf16 v[44:47], v[148:151], v[188:191], v[44:47]
	v_mfma_f32_16x16x32_bf16 v[40:43], v[156:159], v[188:191], v[40:43]
	v_mfma_f32_16x16x32_bf16 v[28:31], v[148:151], v[204:207], v[28:31]
	v_mfma_f32_16x16x32_bf16 v[24:27], v[156:159], v[204:207], v[24:27]
	v_mfma_f32_16x16x32_bf16 v[12:15], v[148:151], v[212:215], v[12:15]
	v_mfma_f32_16x16x32_bf16 v[8:11], v[156:159], v[212:215], v[8:11]
	s_setprio 0
	s_setprio 1
	v_mfma_f32_16x16x32_bf16 v[52:55], v[160:163], v[176:179], v[52:55]
	v_mfma_f32_16x16x32_bf16 v[48:51], v[168:171], v[176:179], v[48:51]
	v_mfma_f32_16x16x32_bf16 v[36:39], v[160:163], v[184:187], v[36:39]
	v_mfma_f32_16x16x32_bf16 v[32:35], v[168:171], v[184:187], v[32:35]
	v_mfma_f32_16x16x32_bf16 v[20:23], v[160:163], v[192:195], v[20:23]
	v_mfma_f32_16x16x32_bf16 v[16:19], v[168:171], v[192:195], v[16:19]
	v_mfma_f32_16x16x32_bf16 v[4:7], v[160:163], v[208:211], v[4:7]
	v_mfma_f32_16x16x32_bf16 v[0:3], v[168:171], v[208:211], v[0:3]
	v_mfma_f32_16x16x32_bf16 v[52:55], v[164:167], v[180:183], v[52:55]
	v_mfma_f32_16x16x32_bf16 v[48:51], v[172:175], v[180:183], v[48:51]
	v_mfma_f32_16x16x32_bf16 v[36:39], v[164:167], v[188:191], v[36:39]
	v_mfma_f32_16x16x32_bf16 v[32:35], v[172:175], v[188:191], v[32:35]
	v_mfma_f32_16x16x32_bf16 v[20:23], v[164:167], v[204:207], v[20:23]
	v_mfma_f32_16x16x32_bf16 v[16:19], v[172:175], v[204:207], v[16:19]
	v_mfma_f32_16x16x32_bf16 v[4:7], v[164:167], v[212:215], v[4:7]
	v_mfma_f32_16x16x32_bf16 v[0:3], v[172:175], v[212:215], v[0:3]
	s_setprio 0
	s_barrier
	s_add_i32 s53, 0, 0x18000
	s_add_i32 s54, 0, 0x1c000
	v_add_u32_e32 v156, s53, v145
	v_add_u32_e32 v172, s54, v145
	ds_read_b128 v[138:141], v156
	ds_read_b128 v[148:151], v156 offset:1024
	ds_read_b128 v[152:155], v156 offset:2048
	ds_read_b128 v[156:159], v156 offset:3072
	ds_read_b128 v[160:163], v172
	ds_read_b128 v[164:167], v172 offset:1024
	ds_read_b128 v[168:171], v172 offset:2048
	ds_read_b128 v[172:175], v172 offset:3072
	s_add_u32 s44, s44, s12
	s_addc_u32 s45, s45, 0
	s_mov_b32 m0, s17
	v_lshl_add_u64 v[230:231], s[44:45], 0, v[132:133]
	ds_read_b128 v[176:179], v147 offset:32768
	ds_read_b128 v[180:183], v147 offset:33792
	ds_read_b128 v[184:187], v147 offset:34816
	ds_read_b128 v[188:191], v147 offset:35840
	ds_read_b128 v[192:195], v147 offset:36864
	ds_read_b128 v[204:207], v147 offset:37888
	ds_read_b128 v[208:211], v147 offset:38912
	ds_read_b128 v[212:215], v147 offset:39936
	global_load_lds_dwordx4 v[230:231], off
	v_lshl_add_u64 v[230:231], s[44:45], 0, v[130:131]
	s_mov_b32 m0, s26
	s_nop 0
	global_load_lds_dwordx4 v[230:231], off
	s_waitcnt vmcnt(8)
	s_waitcnt lgkmcnt(0)
	s_barrier
	s_setprio 1
	s_waitcnt lgkmcnt(0)
	v_mfma_f32_16x16x32_bf16 v[124:127], v[138:141], v[176:179], v[124:127]
	v_mfma_f32_16x16x32_bf16 v[120:123], v[152:155], v[176:179], v[120:123]
	v_mfma_f32_16x16x32_bf16 v[108:111], v[138:141], v[184:187], v[108:111]
	v_mfma_f32_16x16x32_bf16 v[104:107], v[152:155], v[184:187], v[104:107]
	v_mfma_f32_16x16x32_bf16 v[92:95], v[138:141], v[192:195], v[92:95]
	v_mfma_f32_16x16x32_bf16 v[88:91], v[152:155], v[192:195], v[88:91]
	v_mfma_f32_16x16x32_bf16 v[76:79], v[138:141], v[208:211], v[76:79]
	v_mfma_f32_16x16x32_bf16 v[72:75], v[152:155], v[208:211], v[72:75]
	v_mfma_f32_16x16x32_bf16 v[124:127], v[148:151], v[180:183], v[124:127]
	v_mfma_f32_16x16x32_bf16 v[120:123], v[156:159], v[180:183], v[120:123]
	v_mfma_f32_16x16x32_bf16 v[108:111], v[148:151], v[188:191], v[108:111]
	v_mfma_f32_16x16x32_bf16 v[104:107], v[156:159], v[188:191], v[104:107]
	v_mfma_f32_16x16x32_bf16 v[92:95], v[148:151], v[204:207], v[92:95]
	v_mfma_f32_16x16x32_bf16 v[88:91], v[156:159], v[204:207], v[88:91]
	v_mfma_f32_16x16x32_bf16 v[76:79], v[148:151], v[212:215], v[76:79]
	v_mfma_f32_16x16x32_bf16 v[72:75], v[156:159], v[212:215], v[72:75]
	s_setprio 0
	s_setprio 1
	v_mfma_f32_16x16x32_bf16 v[116:119], v[160:163], v[176:179], v[116:119]
	v_mfma_f32_16x16x32_bf16 v[112:115], v[168:171], v[176:179], v[112:115]
	v_mfma_f32_16x16x32_bf16 v[100:103], v[160:163], v[184:187], v[100:103]
	v_mfma_f32_16x16x32_bf16 v[96:99], v[168:171], v[184:187], v[96:99]
	v_mfma_f32_16x16x32_bf16 v[84:87], v[160:163], v[192:195], v[84:87]
	v_mfma_f32_16x16x32_bf16 v[80:83], v[168:171], v[192:195], v[80:83]
	v_mfma_f32_16x16x32_bf16 v[68:71], v[160:163], v[208:211], v[68:71]
	v_mfma_f32_16x16x32_bf16 v[64:67], v[168:171], v[208:211], v[64:67]
	v_mfma_f32_16x16x32_bf16 v[116:119], v[164:167], v[180:183], v[116:119]
	v_mfma_f32_16x16x32_bf16 v[112:115], v[172:175], v[180:183], v[112:115]
	v_mfma_f32_16x16x32_bf16 v[100:103], v[164:167], v[188:191], v[100:103]
	v_mfma_f32_16x16x32_bf16 v[96:99], v[172:175], v[188:191], v[96:99]
	v_mfma_f32_16x16x32_bf16 v[84:87], v[164:167], v[204:207], v[84:87]
	v_mfma_f32_16x16x32_bf16 v[80:83], v[172:175], v[204:207], v[80:83]
	v_mfma_f32_16x16x32_bf16 v[68:71], v[164:167], v[212:215], v[68:71]
	v_mfma_f32_16x16x32_bf16 v[64:67], v[172:175], v[212:215], v[64:67]
	s_setprio 0
	s_barrier
	s_add_i32 s44, s53, s11
	v_lshl_add_u64 v[142:143], v[142:143], 0, s[88:89]
	s_mov_b32 m0, s44
	ds_read_b128 v[176:179], v147 offset:49152
	ds_read_b128 v[180:183], v147 offset:50176
	ds_read_b128 v[184:187], v147 offset:51200
	ds_read_b128 v[188:191], v147 offset:52224
	ds_read_b128 v[192:195], v147 offset:53248
	ds_read_b128 v[204:207], v147 offset:54272
	ds_read_b128 v[208:211], v147 offset:55296
	ds_read_b128 v[212:215], v147 offset:56320
	global_load_lds_dwordx4 v[142:143], off
	v_lshl_add_u64 v[142:143], v[216:217], 0, s[88:89]
	s_add_i32 m0, s44, 0x2000
	s_add_i32 s44, s54, s11
	global_load_lds_dwordx4 v[142:143], off
	v_lshl_add_u64 v[142:143], v[218:219], 0, s[88:89]
	s_mov_b32 m0, s44
	s_nop 0
	global_load_lds_dwordx4 v[142:143], off
	v_lshl_add_u64 v[142:143], v[220:221], 0, s[88:89]
	s_add_i32 m0, s44, 0x2000
	s_nop 0
	global_load_lds_dwordx4 v[142:143], off
	v_lshl_add_u64 v[142:143], v[226:227], 0, s[88:89]
	s_mov_b32 m0, s29
	s_nop 0
	global_load_lds_dwordx4 v[142:143], off
	v_lshl_add_u64 v[142:143], v[228:229], 0, s[88:89]
	s_mov_b32 m0, s33
	s_nop 0
	global_load_lds_dwordx4 v[142:143], off
	s_waitcnt vmcnt(8)
	s_cmp_lt_u32 s52, s28
	s_cbranch_scc1 .Lree2_skip
	v_lshl_add_u32 v234, s51, 8, v144
	v_lshl_or_b32 v232, s36, 8, v146
	v_ashrrev_i32_e32 v235, 31, v234
	v_ashrrev_i32_e32 v233, 31, v232
	v_lshlrev_b64 v[234:235], 11, v[234:235]
	v_lshl_add_u64 v[234:235], s[80:81], 0, v[234:235]
	v_lshl_add_u64 v[254:255], v[232:233], 1, v[234:235]
	v_mov_b32_e32 v240, 0x8000
	v_mov_b32_e32 v241, 0
	global_load_dwordx4 v[232:235], v[254:255], off
	global_load_dwordx4 v[236:239], v[254:255], off offset:256
	v_lshl_add_u64 v[254:255], v[240:241], 0, v[254:255]
	global_load_dwordx4 v[240:243], v[254:255], off
	global_load_dwordx4 v[244:247], v[254:255], off offset:256
.Lree2_skip:
	s_waitcnt lgkmcnt(0)
	s_barrier
	s_setprio 1
	s_waitcnt lgkmcnt(0)
	v_mfma_f32_16x16x32_bf16 v[60:63], v[138:141], v[176:179], v[60:63]
	v_mfma_f32_16x16x32_bf16 v[56:59], v[152:155], v[176:179], v[56:59]
	v_mfma_f32_16x16x32_bf16 v[44:47], v[138:141], v[184:187], v[44:47]
	v_mfma_f32_16x16x32_bf16 v[40:43], v[152:155], v[184:187], v[40:43]
	v_mfma_f32_16x16x32_bf16 v[28:31], v[138:141], v[192:195], v[28:31]
	v_mfma_f32_16x16x32_bf16 v[24:27], v[152:155], v[192:195], v[24:27]
	v_mfma_f32_16x16x32_bf16 v[12:15], v[138:141], v[208:211], v[12:15]
	v_mfma_f32_16x16x32_bf16 v[8:11], v[152:155], v[208:211], v[8:11]
	v_mfma_f32_16x16x32_bf16 v[60:63], v[148:151], v[180:183], v[60:63]
	v_mfma_f32_16x16x32_bf16 v[56:59], v[156:159], v[180:183], v[56:59]
	v_mfma_f32_16x16x32_bf16 v[44:47], v[148:151], v[188:191], v[44:47]
	v_mfma_f32_16x16x32_bf16 v[40:43], v[156:159], v[188:191], v[40:43]
	v_mfma_f32_16x16x32_bf16 v[28:31], v[148:151], v[204:207], v[28:31]
	v_mfma_f32_16x16x32_bf16 v[24:27], v[156:159], v[204:207], v[24:27]
	v_mfma_f32_16x16x32_bf16 v[12:15], v[148:151], v[212:215], v[12:15]
	v_mfma_f32_16x16x32_bf16 v[8:11], v[156:159], v[212:215], v[8:11]
	s_setprio 0
	s_setprio 1
	v_mfma_f32_16x16x32_bf16 v[52:55], v[160:163], v[176:179], v[52:55]
	v_mfma_f32_16x16x32_bf16 v[48:51], v[168:171], v[176:179], v[48:51]
	v_mfma_f32_16x16x32_bf16 v[36:39], v[160:163], v[184:187], v[36:39]
	v_mfma_f32_16x16x32_bf16 v[32:35], v[168:171], v[184:187], v[32:35]
	v_mfma_f32_16x16x32_bf16 v[20:23], v[160:163], v[192:195], v[20:23]
	v_mfma_f32_16x16x32_bf16 v[16:19], v[168:171], v[192:195], v[16:19]
	v_mfma_f32_16x16x32_bf16 v[4:7], v[160:163], v[208:211], v[4:7]
	v_mfma_f32_16x16x32_bf16 v[0:3], v[168:171], v[208:211], v[0:3]
	v_mfma_f32_16x16x32_bf16 v[52:55], v[164:167], v[180:183], v[52:55]
	v_mfma_f32_16x16x32_bf16 v[48:51], v[172:175], v[180:183], v[48:51]
	v_mfma_f32_16x16x32_bf16 v[36:39], v[164:167], v[188:191], v[36:39]
	v_mfma_f32_16x16x32_bf16 v[32:35], v[172:175], v[188:191], v[32:35]
	v_mfma_f32_16x16x32_bf16 v[20:23], v[164:167], v[204:207], v[20:23]
	v_mfma_f32_16x16x32_bf16 v[16:19], v[172:175], v[204:207], v[16:19]
	v_mfma_f32_16x16x32_bf16 v[4:7], v[164:167], v[212:215], v[4:7]
	v_mfma_f32_16x16x32_bf16 v[0:3], v[172:175], v[212:215], v[0:3]
	s_setprio 0
	s_barrier
	s_add_u32 s34, s34, 0x100
	s_addc_u32 s35, s35, 0
	s_add_u32 s46, s46, 0x100
	s_addc_u32 s47, s47, 0
	s_cmp_ge_u32 s52, s28
	s_mov_b32 s44, s52
	s_cbranch_scc0 .LBB0_855
	s_and_b64 vcc, exec, s[22:23]
	s_cbranch_vccz .LBB0_858
	s_barrier
.LBB0_858:
	v_lshl_add_u32 v140, s51, 8, v144
	v_ashrrev_i32_e32 v141, 31, v140
	v_lshl_or_b32 v138, s36, 8, v146
	v_lshlrev_b64 v[142:143], 11, v[140:141]
	v_ashrrev_i32_e32 v139, 31, v138
	v_lshl_add_u64 v[142:143], s[80:81], 0, v[142:143]
	v_lshl_add_u64 v[142:143], v[138:139], 1, v[142:143]
	s_mov_b64 s[52:53], 0x10000
	v_lshl_add_u64 v[226:227], s[52:53], 0, v[142:143]
	global_load_dwordx4 v[168:171], v[226:227], off
	global_load_dwordx4 v[172:175], v[226:227], off offset:256
	s_mov_b64 s[52:53], 0x18000
	v_lshl_add_u64 v[226:227], s[52:53], 0, v[142:143]
	global_load_dwordx4 v[176:179], v[226:227], off
	global_load_dwordx4 v[180:183], v[226:227], off offset:256
	s_mov_b64 s[52:53], 0x40000
	v_lshl_add_u64 v[226:227], s[52:53], 0, v[142:143]
	global_load_dwordx4 v[184:187], v[226:227], off
	global_load_dwordx4 v[188:191], v[226:227], off offset:256
	s_mov_b64 s[52:53], 0x48000
	v_lshl_add_u64 v[226:227], s[52:53], 0, v[142:143]
	global_load_dwordx4 v[192:195], v[226:227], off
	global_load_dwordx4 v[204:207], v[226:227], off offset:256
	s_mov_b64 s[52:53], 0x50000
	v_lshl_add_u64 v[226:227], s[52:53], 0, v[142:143]
	global_load_dwordx4 v[208:211], v[226:227], off
	global_load_dwordx4 v[212:215], v[226:227], off offset:256
	s_mov_b64 s[52:53], 0x58000
	v_lshl_add_u64 v[226:227], s[52:53], 0, v[142:143]
	global_load_dwordx4 v[216:219], v[226:227], off
	global_load_dwordx4 v[228:231], v[226:227], off offset:256
	s_lshl_b32 s34, s36, 2
	s_ashr_i32 s35, s34, 31
	s_waitcnt vmcnt(12)
	v_mov_b64_e32 v[148:149], v[232:233]
	v_mov_b64_e32 v[150:151], v[234:235]
	v_mov_b64_e32 v[156:157], v[236:237]
	v_mov_b64_e32 v[158:159], v[238:239]
	v_mov_b64_e32 v[160:161], v[240:241]
	v_mov_b64_e32 v[162:163], v[242:243]
	v_mov_b64_e32 v[164:165], v[244:245]
	v_mov_b64_e32 v[166:167], v[246:247]
	s_waitcnt vmcnt(15)
	v_lshlrev_b32_e32 v152, 16, v148
	v_fmac_f32_e32 v152, s2, v124
	v_and_b32_e32 v124, 0xffff0000, v148
	v_fmac_f32_e32 v124, s2, v125
	v_cvt_pk_bf16_f32 v124, v152, v124
	s_nop 0
	v_and_b32_e32 v148, 0xffff0000, v124
	v_lshlrev_b32_e32 v125, 16, v124
	v_mul_f32_e32 v148, v148, v148
	v_fmac_f32_e32 v148, v125, v125
	v_lshlrev_b32_e32 v125, 16, v149
	v_fmac_f32_e32 v125, s2, v126
	v_and_b32_e32 v126, 0xffff0000, v149
	v_fmac_f32_e32 v126, s2, v127
	v_cvt_pk_bf16_f32 v125, v125, v126
	s_nop 0
	v_and_b32_e32 v127, 0xffff0000, v125
	v_lshlrev_b32_e32 v126, 16, v125
	v_mul_f32_e32 v127, v127, v127
	v_fmac_f32_e32 v127, v126, v126
	v_lshlrev_b32_e32 v126, 16, v150
	v_fmac_f32_e32 v126, s2, v120
	v_and_b32_e32 v120, 0xffff0000, v150
	v_fmac_f32_e32 v120, s2, v121
	v_cvt_pk_bf16_f32 v126, v126, v120
	v_add_f32_e32 v127, v148, v127
	v_and_b32_e32 v121, 0xffff0000, v126
	v_lshlrev_b32_e32 v120, 16, v126
	v_mul_f32_e32 v121, v121, v121
	v_fmac_f32_e32 v121, v120, v120
	v_add_f32_e32 v120, v127, v121
	v_lshlrev_b32_e32 v121, 16, v151
	v_fmac_f32_e32 v121, s2, v122
	v_and_b32_e32 v122, 0xffff0000, v151
	v_fmac_f32_e32 v122, s2, v123
	v_cvt_pk_bf16_f32 v127, v121, v122
	global_store_dwordx4 v[142:143], v[124:127], off
	v_and_b32_e32 v122, 0xffff0000, v127
	v_lshlrev_b32_e32 v121, 16, v127
	v_mul_f32_e32 v122, v122, v122
	v_fmac_f32_e32 v122, v121, v121
	v_add_f32_e32 v148, v120, v122
	s_waitcnt vmcnt(15)
	v_mov_b64_e32 v[120:121], v[156:157]
	v_mov_b64_e32 v[122:123], v[158:159]
	v_lshlrev_b32_e32 v124, 16, v120
	v_fmac_f32_e32 v124, s2, v116
	v_and_b32_e32 v116, 0xffff0000, v120
	v_fmac_f32_e32 v116, s2, v117
	v_cvt_pk_bf16_f32 v116, v124, v116
	s_nop 0
	v_and_b32_e32 v120, 0xffff0000, v116
	v_lshlrev_b32_e32 v117, 16, v116
	v_mul_f32_e32 v120, v120, v120
	v_fmac_f32_e32 v120, v117, v117
	v_lshlrev_b32_e32 v117, 16, v121
	v_fmac_f32_e32 v117, s2, v118
	v_and_b32_e32 v118, 0xffff0000, v121
	v_fmac_f32_e32 v118, s2, v119
	v_cvt_pk_bf16_f32 v117, v117, v118
	v_add_f32_e32 v120, v148, v120
	v_and_b32_e32 v119, 0xffff0000, v117
	v_lshlrev_b32_e32 v118, 16, v117
	v_mul_f32_e32 v119, v119, v119
	v_fmac_f32_e32 v119, v118, v118
	v_lshlrev_b32_e32 v118, 16, v122
	v_fmac_f32_e32 v118, s2, v112
	v_and_b32_e32 v112, 0xffff0000, v122
	v_fmac_f32_e32 v112, s2, v113
	v_cvt_pk_bf16_f32 v118, v118, v112
	v_add_f32_e32 v119, v120, v119
	v_and_b32_e32 v113, 0xffff0000, v118
	v_lshlrev_b32_e32 v112, 16, v118
	v_mul_f32_e32 v113, v113, v113
	v_fmac_f32_e32 v113, v112, v112
	v_add_f32_e32 v112, v119, v113
	v_lshlrev_b32_e32 v113, 16, v123
	v_fmac_f32_e32 v113, s2, v114
	v_and_b32_e32 v114, 0xffff0000, v123
	v_fmac_f32_e32 v114, s2, v115
	v_cvt_pk_bf16_f32 v119, v113, v114
	global_store_dwordx4 v[142:143], v[116:119], off offset:256
	v_and_b32_e32 v114, 0xffff0000, v119
	v_lshlrev_b32_e32 v113, 16, v119
	v_mul_f32_e32 v114, v114, v114
	v_fmac_f32_e32 v114, v113, v113
	v_add_f32_e32 v112, v112, v114
	v_and_b32_e32 v114, 64, v222
	v_xor_b32_e32 v113, 16, v222
	v_add_u32_e32 v115, 64, v114
	v_cmp_lt_i32_e32 vcc, v113, v115
	s_nop 1
	v_cndmask_b32_e32 v113, v222, v113, vcc
	v_lshlrev_b32_e32 v114, 2, v113
	v_mov_b32_e32 v113, v112
	s_nop 1
	v_permlane16_swap_b32_e32 v112, v113
	s_waitcnt lgkmcnt(0)
	v_add_f32_e32 v112, v112, v113
	v_xor_b32_e32 v113, 32, v222
	v_cmp_lt_i32_e32 vcc, v113, v115
	s_nop 1
	v_cndmask_b32_e32 v113, v222, v113, vcc
	v_lshlrev_b32_e32 v115, 2, v113
	v_mov_b32_e32 v113, v112
	s_nop 1
	v_permlane32_swap_b32_e32 v112, v113
	s_and_saveexec_b64 s[44:45], s[40:41]
	s_cbranch_execz .LBB0_860
	v_lshlrev_b64 v[116:117], 6, v[140:141]
	v_lshl_add_u64 v[116:117], s[20:21], 0, v[116:117]
	v_lshl_add_u64 v[116:117], s[34:35], 2, v[116:117]
	s_lshl_b32 s36, s27, 2
	v_lshl_add_u64 v[116:117], v[116:117], 0, s[36:37]
	s_waitcnt lgkmcnt(0)
	v_add_f32_e32 v112, v112, v113
	global_store_dword v[116:117], v112, off
